# hgrn_out: chunk-state gather two groups in flight; readout wave-sum via DPP + permlane16 instead of five ds_swizzle round trips
# speedup vs baseline: 1.0127x; 1.0127x over previous
; __device__ __forceinline__ float bf2f(unsigned v) { return __uint_as_float(v << 16); }
; __device__ __forceinline__ unsigned f2bf(float f) { return pk2(f, 0.f) & 0xffffu; }
; template <int K> __device__ __forceinline__ float swz_xor(float v) { return __uint_as_float((unsigned)__builtin_amdgcn_ds_swizzle((int)__float_as_uint(v), (K << 10) | 0x1f)); }
; __device__ __forceinline__ float xor32_sum(float v) { const auto rr = __builtin_amdgcn_permlane32_swap(__float_as_uint(v), __float_as_uint(v), false, false); return __uint_as_float(rr[0]) + __uint_as_float(rr[1]); }
; __device__ __forceinline__ float siluf_(float x) { return x * __builtin_amdgcn_rcpf(1.0f + __builtin_amdgcn_exp2f(-1.4426950408889634f * x)); }
; __device__ __forceinline__ float wave_sum(float v) {
;     v += swz_xor<1>(v); v += swz_xor<2>(v); v += swz_xor<4>(v); v += swz_xor<8>(v); v += swz_xor<16>(v);
;     return xor32_sum(v);
; __device__ __forceinline__ void hgrn_out_phase(const Ctx& F, const Args& a, int l) {
;     ...
; #pragma unroll 4
;             for (int k = 0; k < 32; ++k) {
;                 const int tt = 32 * dir + k;
;                 const float ot = ob_f[tt * 64 + lane] + ob_b[tt * 64 + lane];
;                 const float ss = wave_sum(ot * ot);
;                 const float gg = bf2f(PB[(size_t)(rb + tt) * INW + C_BG + head * 64 + lane]);
;                 const float y = ot * (1.0f / sqrtf(ss * (1.f / 64.f) + EPSN)) * og * siluf_(gg);
;                 Y[(size_t)(rb + tt) * D + 256 + head * 64 + lane] = (bf16_t)f2bf(y);
;             }
.LBB0_314:
	v_add_u32_e32 v4, s6, v0
	v_add_u32_e32 v5, 0x14000, v4
	ds_read2st64_b32 v[2:3], v4 offset0:32 offset1:33
	ds_read_b32 v5, v5
	s_add_i32 s22, s44, -3
	s_ashr_i32 s23, s22, 31
	s_add_i32 s82, s44, -1
	s_ashr_i32 s83, s82, 31
	s_waitcnt lgkmcnt(0)
	v_add_f32_e32 v2, v2, v5
	v_mul_f32_e32 v5, v2, v2
	s_nop 1
	v_mov_b32_dpp v5, v5 quad_perm:[1,0,3,2] row_mask:0xf bank_mask:0xf
	s_ashr_i32 s45, s44, 31
	s_addk_i32 s6, 0x400
	s_waitcnt lgkmcnt(0)
	v_fmac_f32_e32 v5, v2, v2
	s_nop 1
	v_mov_b32_dpp v6, v5 quad_perm:[2,3,0,1] row_mask:0xf bank_mask:0xf
	s_waitcnt lgkmcnt(0)
	v_add_f32_e32 v5, v5, v6
	s_nop 1
	v_mov_b32_dpp v6, v5 row_half_mirror row_mask:0xf bank_mask:0xf
	s_waitcnt lgkmcnt(0)
	v_add_f32_e32 v5, v5, v6
	s_nop 1
	v_mov_b32_dpp v6, v5 row_ror:8 row_mask:0xf bank_mask:0xf
	s_waitcnt lgkmcnt(0)
	v_add_f32_e32 v5, v5, v6
	v_mov_b32_e32 v6, v5
	s_nop 1
	v_permlane16_swap_b32_e32 v5, v6
	s_waitcnt lgkmcnt(0)
	v_add_f32_e32 v5, v5, v6
	v_mov_b32_e32 v6, v5
	s_nop 1
	v_permlane32_swap_b32_e32 v5, v6
	v_add_f32_e32 v5, v5, v6
	v_mad_i64_i32 v[6:7], s[4:5], s22, v205, v[116:117]
	global_load_ushort v6, v[6:7], off offset:3072
	v_fmamk_f32 v5, v5, 0x3c800000, v193
	v_cmp_gt_f32_e32 vcc, s41, v5
	s_waitcnt vmcnt(0)
	v_lshlrev_b32_e32 v7, 16, v6
	v_mul_f32_e32 v6, 0x4f800000, v5
	v_cndmask_b32_e32 v5, v5, v6, vcc
	v_sqrt_f32_e32 v6, v5
	s_nop 0
	v_add_u32_e32 v8, -1, v6
	v_fma_f32 v9, -v8, v6, v5
	v_cmp_ge_f32_e64 s[4:5], 0, v9
	v_add_u32_e32 v9, 1, v6
	s_nop 0
	v_cndmask_b32_e64 v8, v6, v8, s[4:5]
	v_fma_f32 v6, -v9, v6, v5
	v_cmp_lt_f32_e64 s[4:5], 0, v6
	s_nop 1
	v_cndmask_b32_e64 v6, v8, v9, s[4:5]
	v_mul_f32_e32 v8, 0x37800000, v6
	v_cndmask_b32_e32 v6, v6, v8, vcc
	v_cmp_class_f32_e32 vcc, v5, v202
	s_nop 1
	v_cndmask_b32_e32 v5, v6, v5, vcc
	v_div_scale_f32 v6, s[4:5], v5, v5, 1.0
	v_rcp_f32_e32 v8, v6
	s_lshl_b64 s[4:5], s[22:23], 11
	s_add_i32 s22, s44, -2
	s_ashr_i32 s23, s22, 31
	v_fma_f32 v9, -v6, v8, 1.0
	v_fmac_f32_e32 v8, v9, v8
	v_div_scale_f32 v9, vcc, 1.0, v5, 1.0
	v_mul_f32_e32 v10, v9, v8
	v_fma_f32 v11, -v6, v10, v9
	v_fmac_f32_e32 v10, v11, v8
	v_fma_f32 v6, -v6, v10, v9
	v_div_fmas_f32 v6, v6, v8, v10
	v_div_fixup_f32 v5, v6, v5, 1.0
	v_mul_f32_e32 v6, v2, v5
	v_mul_f32_e32 v2, 0xbfb8aa3b, v7
	v_exp_f32_e32 v2, v2
	s_nop 0
	v_add_f32_e32 v2, 1.0, v2
	v_rcp_f32_e32 v99, v2
	s_nop 0
	v_pk_mul_f32 v[6:7], v[98:99], v[6:7]
	s_nop 0
	v_mul_f32_e32 v2, v6, v7
	v_cvt_pk_bf16_f32 v2, v2, s0
	v_lshl_add_u64 v[6:7], v[112:113], 0, s[4:5]
	global_store_short v[6:7], v2, off
	v_add_u32_e32 v2, 0x14100, v4
	ds_read_b32 v2, v2
	s_waitcnt lgkmcnt(0)
	v_add_f32_e32 v5, v3, v2
	v_mul_f32_e32 v2, v5, v5
	s_nop 1
	v_mov_b32_dpp v2, v2 quad_perm:[1,0,3,2] row_mask:0xf bank_mask:0xf
	s_waitcnt lgkmcnt(0)
	v_fmac_f32_e32 v2, v5, v5
	s_nop 1
	v_mov_b32_dpp v3, v2 quad_perm:[2,3,0,1] row_mask:0xf bank_mask:0xf
	s_waitcnt lgkmcnt(0)
	v_add_f32_e32 v2, v2, v3
	s_nop 1
	v_mov_b32_dpp v3, v2 row_half_mirror row_mask:0xf bank_mask:0xf
	s_waitcnt lgkmcnt(0)
	v_add_f32_e32 v2, v2, v3
	s_nop 1
	v_mov_b32_dpp v3, v2 row_ror:8 row_mask:0xf bank_mask:0xf
	s_waitcnt lgkmcnt(0)
	v_add_f32_e32 v2, v2, v3
	v_mov_b32_e32 v3, v2
	s_nop 1
	v_permlane16_swap_b32_e32 v2, v3
	s_waitcnt lgkmcnt(0)
	v_add_f32_e32 v2, v2, v3
	v_mov_b32_e32 v3, v2
	s_nop 1
	v_permlane32_swap_b32_e32 v2, v3
	v_add_f32_e32 v6, v2, v3
	v_mad_i64_i32 v[2:3], s[4:5], s22, v205, v[116:117]
	global_load_ushort v2, v[2:3], off offset:3072
	s_waitcnt vmcnt(0)
	v_lshlrev_b32_e32 v3, 16, v2
	v_fmamk_f32 v2, v6, 0x3c800000, v193
	v_cmp_gt_f32_e32 vcc, s41, v2
	v_mul_f32_e32 v6, 0x4f800000, v2
	s_nop 0
	v_cndmask_b32_e32 v2, v2, v6, vcc
	v_sqrt_f32_e32 v6, v2
	s_nop 0
	v_add_u32_e32 v7, -1, v6
	v_fma_f32 v8, -v7, v6, v2
	v_cmp_ge_f32_e64 s[4:5], 0, v8
	v_add_u32_e32 v8, 1, v6
	s_nop 0
	v_cndmask_b32_e64 v7, v6, v7, s[4:5]
	v_fma_f32 v6, -v8, v6, v2
	v_cmp_lt_f32_e64 s[4:5], 0, v6
	s_nop 1
	v_cndmask_b32_e64 v6, v7, v8, s[4:5]
	v_mul_f32_e32 v7, 0x37800000, v6
	v_cndmask_b32_e32 v6, v6, v7, vcc
	v_cmp_class_f32_e32 vcc, v2, v202
	s_nop 1
	v_cndmask_b32_e32 v2, v6, v2, vcc
	v_div_scale_f32 v6, s[4:5], v2, v2, 1.0
	v_rcp_f32_e32 v7, v6
	s_lshl_b64 s[4:5], s[22:23], 11
	v_fma_f32 v8, -v6, v7, 1.0
	v_fmac_f32_e32 v7, v8, v7
	v_div_scale_f32 v8, vcc, 1.0, v2, 1.0
	v_mul_f32_e32 v9, v8, v7
	v_fma_f32 v10, -v6, v9, v8
	v_fmac_f32_e32 v9, v10, v7
	v_fma_f32 v6, -v6, v9, v8
	v_div_fmas_f32 v6, v6, v7, v9
	v_div_fixup_f32 v2, v6, v2, 1.0
	v_mul_f32_e32 v2, v5, v2
	v_mul_f32_e32 v5, 0xbfb8aa3b, v3
	v_exp_f32_e32 v5, v5
	s_nop 0
	v_add_f32_e32 v5, 1.0, v5
	v_rcp_f32_e32 v99, v5
	s_nop 0
	v_pk_mul_f32 v[2:3], v[98:99], v[2:3]
	s_nop 0
	v_mul_f32_e32 v2, v2, v3
	v_cvt_pk_bf16_f32 v5, v2, s0
	v_lshl_add_u64 v[2:3], v[112:113], 0, s[4:5]
	global_store_short v[2:3], v5, off
	v_add_u32_e32 v5, 0x14200, v4
	ds_read2st64_b32 v[2:3], v4 offset0:34 offset1:35
	ds_read_b32 v5, v5
	s_waitcnt lgkmcnt(0)
; __device__ __forceinline__ float bf2f(unsigned v) { return __uint_as_float(v << 16); }
; __device__ __forceinline__ unsigned f2bf(float f) { return pk2(f, 0.f) & 0xffffu; }
; __device__ __forceinline__ float siluf_(float x) { return x * __builtin_amdgcn_rcpf(1.0f + __builtin_amdgcn_exp2f(-1.4426950408889634f * x)); }
; __device__ __forceinline__ void hgrn_out_phase(const Ctx& F, const Args& a, int l) {
;     ...
; #pragma unroll 4
;             for (int k = 0; k < 32; ++k) {
;                 const int tt = 32 * dir + k;
;                 const float ot = ob_f[tt * 64 + lane] + ob_b[tt * 64 + lane];
;                 const float ss = wave_sum(ot * ot);
;                 const float gg = bf2f(PB[(size_t)(rb + tt) * INW + C_BG + head * 64 + lane]);
;                 const float y = ot * (1.0f / sqrtf(ss * (1.f / 64.f) + EPSN)) * og * siluf_(gg);
;                 Y[(size_t)(rb + tt) * D + 256 + head * 64 + lane] = (bf16_t)f2bf(y);
;             }
;         }
;         __syncthreads();
;     }
	v_add_f32_e32 v2, v2, v5
	v_mul_f32_e32 v5, v2, v2
	s_nop 1
	v_mov_b32_dpp v5, v5 quad_perm:[1,0,3,2] row_mask:0xf bank_mask:0xf
	s_waitcnt lgkmcnt(0)
	v_fmac_f32_e32 v5, v2, v2
	s_nop 1
	v_mov_b32_dpp v6, v5 quad_perm:[2,3,0,1] row_mask:0xf bank_mask:0xf
	s_waitcnt lgkmcnt(0)
	v_add_f32_e32 v5, v5, v6
	s_nop 1
	v_mov_b32_dpp v6, v5 row_half_mirror row_mask:0xf bank_mask:0xf
	s_waitcnt lgkmcnt(0)
	v_add_f32_e32 v5, v5, v6
	s_nop 1
	v_mov_b32_dpp v6, v5 row_ror:8 row_mask:0xf bank_mask:0xf
	s_waitcnt lgkmcnt(0)
	v_add_f32_e32 v5, v5, v6
	v_mov_b32_e32 v6, v5
	s_nop 1
	v_permlane16_swap_b32_e32 v5, v6
	s_waitcnt lgkmcnt(0)
	v_add_f32_e32 v5, v5, v6
	v_mov_b32_e32 v6, v5
	s_nop 1
	v_permlane32_swap_b32_e32 v5, v6
	v_add_f32_e32 v5, v5, v6
	v_mad_i64_i32 v[6:7], s[4:5], s82, v205, v[116:117]
	global_load_ushort v6, v[6:7], off offset:3072
	v_fmamk_f32 v5, v5, 0x3c800000, v193
	v_cmp_gt_f32_e32 vcc, s41, v5
	s_waitcnt vmcnt(0)
	v_lshlrev_b32_e32 v7, 16, v6
	v_mul_f32_e32 v6, 0x4f800000, v5
	v_cndmask_b32_e32 v5, v5, v6, vcc
	v_sqrt_f32_e32 v6, v5
	s_nop 0
	v_add_u32_e32 v8, -1, v6
	v_fma_f32 v9, -v8, v6, v5
	v_cmp_ge_f32_e64 s[4:5], 0, v9
	v_add_u32_e32 v9, 1, v6
	s_nop 0
	v_cndmask_b32_e64 v8, v6, v8, s[4:5]
	v_fma_f32 v6, -v9, v6, v5
	v_cmp_lt_f32_e64 s[4:5], 0, v6
	s_nop 1
	v_cndmask_b32_e64 v6, v8, v9, s[4:5]
	v_mul_f32_e32 v8, 0x37800000, v6
	v_cndmask_b32_e32 v6, v6, v8, vcc
	v_cmp_class_f32_e32 vcc, v5, v202
	s_nop 1
	v_cndmask_b32_e32 v5, v6, v5, vcc
	v_div_scale_f32 v6, s[4:5], v5, v5, 1.0
	v_rcp_f32_e32 v8, v6
	s_lshl_b64 s[4:5], s[82:83], 11
	v_fma_f32 v9, -v6, v8, 1.0
	v_fmac_f32_e32 v8, v9, v8
	v_div_scale_f32 v9, vcc, 1.0, v5, 1.0
	v_mul_f32_e32 v10, v9, v8
	v_fma_f32 v11, -v6, v10, v9
	v_fmac_f32_e32 v10, v11, v8
	v_fma_f32 v6, -v6, v10, v9
	v_div_fmas_f32 v6, v6, v8, v10
	v_div_fixup_f32 v5, v6, v5, 1.0
	v_mul_f32_e32 v6, v2, v5
	v_mul_f32_e32 v2, 0xbfb8aa3b, v7
	v_exp_f32_e32 v2, v2
	s_nop 0
	v_add_f32_e32 v2, 1.0, v2
	v_rcp_f32_e32 v99, v2
	s_nop 0
	v_pk_mul_f32 v[6:7], v[98:99], v[6:7]
	s_nop 0
	v_mul_f32_e32 v2, v6, v7
	v_cvt_pk_bf16_f32 v2, v2, s0
	v_lshl_add_u64 v[6:7], v[112:113], 0, s[4:5]
	global_store_short v[6:7], v2, off
	v_add_u32_e32 v2, 0x14300, v4
	ds_read_b32 v2, v2
	s_waitcnt lgkmcnt(0)
	v_add_f32_e32 v2, v3, v2
	v_mul_f32_e32 v3, v2, v2
	s_nop 1
	v_mov_b32_dpp v3, v3 quad_perm:[1,0,3,2] row_mask:0xf bank_mask:0xf
	s_waitcnt lgkmcnt(0)
	v_fmac_f32_e32 v3, v2, v2
	s_nop 1
	v_mov_b32_dpp v4, v3 quad_perm:[2,3,0,1] row_mask:0xf bank_mask:0xf
	s_waitcnt lgkmcnt(0)
	v_add_f32_e32 v3, v3, v4
	s_nop 1
	v_mov_b32_dpp v4, v3 row_half_mirror row_mask:0xf bank_mask:0xf
	s_waitcnt lgkmcnt(0)
	v_add_f32_e32 v3, v3, v4
	s_nop 1
	v_mov_b32_dpp v4, v3 row_ror:8 row_mask:0xf bank_mask:0xf
	s_waitcnt lgkmcnt(0)
	v_add_f32_e32 v3, v3, v4
	v_mov_b32_e32 v4, v3
	s_nop 1
	v_permlane16_swap_b32_e32 v3, v4
	s_waitcnt lgkmcnt(0)
	v_add_f32_e32 v3, v3, v4
	v_mov_b32_e32 v4, v3
	s_nop 1
	v_permlane32_swap_b32_e32 v3, v4
	v_add_f32_e32 v6, v3, v4
	v_mad_i64_i32 v[4:5], s[4:5], s44, v205, v[116:117]
	global_load_ushort v3, v[4:5], off offset:3072
	v_fmamk_f32 v4, v6, 0x3c800000, v193
	v_cmp_gt_f32_e32 vcc, s41, v4
	v_mul_f32_e32 v5, 0x4f800000, v4
	s_waitcnt vmcnt(0)
	v_lshlrev_b32_e32 v3, 16, v3
	v_cndmask_b32_e32 v4, v4, v5, vcc
	v_sqrt_f32_e32 v5, v4
	s_nop 0
	v_add_u32_e32 v6, -1, v5
	v_fma_f32 v7, -v6, v5, v4
	v_cmp_ge_f32_e64 s[4:5], 0, v7
	v_add_u32_e32 v7, 1, v5
	s_nop 0
	v_cndmask_b32_e64 v6, v5, v6, s[4:5]
	v_fma_f32 v5, -v7, v5, v4
	v_cmp_lt_f32_e64 s[4:5], 0, v5
	s_nop 1
	v_cndmask_b32_e64 v5, v6, v7, s[4:5]
	v_mul_f32_e32 v6, 0x37800000, v5
	v_cndmask_b32_e32 v5, v5, v6, vcc
	v_cmp_class_f32_e32 vcc, v4, v202
	s_nop 1
	v_cndmask_b32_e32 v4, v5, v4, vcc
	v_div_scale_f32 v5, s[4:5], v4, v4, 1.0
	v_rcp_f32_e32 v6, v5
	s_lshl_b64 s[4:5], s[44:45], 11
	s_add_i32 s44, s44, 4
	s_cmp_eq_u32 s6, 0
	v_fma_f32 v7, -v5, v6, 1.0
	v_fmac_f32_e32 v6, v7, v6
	v_div_scale_f32 v7, vcc, 1.0, v4, 1.0
	v_mul_f32_e32 v8, v7, v6
	v_fma_f32 v9, -v5, v8, v7
	v_fmac_f32_e32 v8, v9, v6
	v_fma_f32 v5, -v5, v8, v7
	v_div_fmas_f32 v5, v5, v6, v8
	v_div_fixup_f32 v4, v5, v4, 1.0
	v_mul_f32_e32 v2, v2, v4
	v_mul_f32_e32 v4, 0xbfb8aa3b, v3
	v_exp_f32_e32 v4, v4
	s_nop 0
	v_add_f32_e32 v4, 1.0, v4
	v_rcp_f32_e32 v99, v4
	s_nop 0
	v_pk_mul_f32 v[2:3], v[98:99], v[2:3]
	s_nop 0
	v_mul_f32_e32 v2, v2, v3
	v_cvt_pk_bf16_f32 v4, v2, s0
	v_lshl_add_u64 v[2:3], v[112:113], 0, s[4:5]
	global_store_short v[2:3], v4, off
	s_cbranch_scc0 .LBB0_314
	s_addk_i32 s84, 0x270
	s_nop 0
	s_addk_i32 s85, 0x2700
	s_nop 0
	v_readlane_b32 s66, v253, 19
	v_readlane_b32 s46, v253, 24
	v_readlane_b32 s52, v253, 26
	s_sub_i32 s2, s84, 0x400
	s_cmp_gt_u32 s2, 15
	s_mov_b32 s93, 0xff61b1e6
	s_mov_b32 s94, 0xc2ce8ed0
	s_mov_b32 s95, 0x42b17218
	s_mov_b32 s36, 0x3fb8aa3b
	v_readlane_b32 s67, v253, 20
	v_readlane_b32 s47, v253, 25
	v_readlane_b32 s53, v253, 27
	s_barrier
	s_cbranch_scc0 .LBB0_313
